# in-proj GEMM per-tile accumulator clear with 64-bit moves (half the instructions)
# speedup vs baseline: 1.0066x; 1.0066x over previous
.LBB0_610:
	v_mov_b32_e32 v0, 0
	s_mov_b32 s90, s52
	s_mov_b32 s62, s54
	s_mov_b64 s[58:59], s[86:87]
	s_mov_b64 s[56:57], s[74:75]
	s_mov_b32 s35, s36
	v_mov_b32_e32 v1, v0
	v_mov_b64_e32 v[2:3], v[0:1]
	v_mov_b64_e32 v[4:5], v[0:1]
	v_mov_b64_e32 v[6:7], v[0:1]
	v_mov_b64_e32 v[8:9], v[0:1]
	v_mov_b64_e32 v[10:11], v[0:1]
	v_mov_b64_e32 v[12:13], v[0:1]
	v_mov_b64_e32 v[14:15], v[0:1]
	v_mov_b64_e32 v[16:17], v[0:1]
	v_mov_b64_e32 v[18:19], v[0:1]
	v_mov_b64_e32 v[20:21], v[0:1]
	v_mov_b64_e32 v[22:23], v[0:1]
	v_mov_b64_e32 v[24:25], v[0:1]
	v_mov_b64_e32 v[26:27], v[0:1]
	v_mov_b64_e32 v[28:29], v[0:1]
	v_mov_b64_e32 v[30:31], v[0:1]
	v_mov_b64_e32 v[32:33], v[0:1]
	v_mov_b64_e32 v[34:35], v[0:1]
	v_mov_b64_e32 v[36:37], v[0:1]
	v_mov_b64_e32 v[38:39], v[0:1]
	v_mov_b64_e32 v[40:41], v[0:1]
	v_mov_b64_e32 v[42:43], v[0:1]
	v_mov_b64_e32 v[44:45], v[0:1]
	v_mov_b64_e32 v[46:47], v[0:1]
	v_mov_b64_e32 v[50:51], v[0:1]
	v_mov_b64_e32 v[52:53], v[0:1]
	v_mov_b64_e32 v[54:55], v[0:1]
	v_mov_b64_e32 v[56:57], v[0:1]
	v_mov_b64_e32 v[58:59], v[0:1]
	v_mov_b64_e32 v[60:61], v[0:1]
	v_mov_b64_e32 v[62:63], v[0:1]
	v_mov_b64_e32 v[64:65], v[0:1]
	v_mov_b64_e32 v[66:67], v[0:1]
	v_mov_b64_e32 v[68:69], v[0:1]
	v_mov_b64_e32 v[70:71], v[0:1]
	v_mov_b64_e32 v[72:73], v[0:1]
	v_mov_b64_e32 v[74:75], v[0:1]
	v_mov_b64_e32 v[76:77], v[0:1]
	v_mov_b64_e32 v[78:79], v[0:1]
	v_mov_b64_e32 v[80:81], v[0:1]
	v_mov_b64_e32 v[82:83], v[0:1]
	v_mov_b64_e32 v[84:85], v[0:1]
	v_mov_b64_e32 v[86:87], v[0:1]
	v_mov_b64_e32 v[88:89], v[0:1]
	v_mov_b64_e32 v[90:91], v[0:1]
	v_mov_b64_e32 v[92:93], v[0:1]
	v_mov_b64_e32 v[94:95], v[0:1]
	v_mov_b64_e32 v[96:97], v[0:1]
	v_mov_b64_e32 v[98:99], v[0:1]
	v_mov_b64_e32 v[100:101], v[0:1]
	v_mov_b64_e32 v[102:103], v[0:1]
	v_mov_b64_e32 v[104:105], v[0:1]
	v_mov_b64_e32 v[106:107], v[0:1]
	v_mov_b64_e32 v[108:109], v[0:1]
	v_mov_b64_e32 v[110:111], v[0:1]
	v_mov_b64_e32 v[112:113], v[0:1]
	v_mov_b64_e32 v[114:115], v[0:1]
	v_mov_b64_e32 v[116:117], v[0:1]
	v_mov_b64_e32 v[118:119], v[0:1]
	v_mov_b64_e32 v[120:121], v[0:1]
	v_mov_b64_e32 v[122:123], v[0:1]
	v_mov_b64_e32 v[124:125], v[0:1]
	v_mov_b64_e32 v[126:127], v[0:1]
	v_mov_b64_e32 v[128:129], v[0:1]
	s_branch .LBB0_342
